# v25 + ATTB unit-top wait vmcnt(8) instead of full drain
# baseline (speedup 1.0000x reference)
; #define LAS __attribute__((address_space(3)))
; #define ATT_ROWDMA(KR, VR, ROW, SLOT) do { const unsigned sl_ = (unsigned)__builtin_amdgcn_readfirstlane((int)(ringb + (unsigned)(SLOT) * RING_SLOT)); \
;         glds16_asm((const char*)((KR) + (size_t)(ROW) * 4096) + kSrc, sl_ + kDst); glds16_asm((const char*)((VR) + (size_t)(ROW) * 4096) + vSrc, sl_ + vDst); } while (0)
; #define ATT_QLOADB(U) do { const bf16* qa_ = qkv + ((size_t)((U).b * 16 + (U).h) * 4096 + 512 * (U).R + (2 * wq + (q >> 4)) * 64 + gcq) * 64; \
;         _Pragma("unroll") for (int d0 = 0; d0 < 4; ++d0) { st.qA[d0] = *(const bf16x8*)(qa_ + d0 * 16 + hi * 8); st.qB[d0] = *(const bf16x8*)(qa_ + 256 * 64 + d0 * 16 + hi * 8); } } while (0)
; __device__ __forceinline__ void attn_b_phase(Frame& F, const float cshift, const bf16* qkv, const bf16* gate, bf16* y, const float* rpb, const float* qg, const float* kg) {
;     ...
;     const int wq = wave >> 2, cb = wave & 3, q = lane & 31, hi = lane >> 5;
;     const int gcq = 16 * cb + (q & 15), slab0 = min(max(16 * cb - 8, 0), 32), csq = min(max(gcq - 8, 0), 48);
;     float cm[16];
; #pragma unroll
;     for (int r = 0; r < 16; ++r) { const int kc = slab0 + (r & 3) + 8 * (r >> 2) + 4 * hi; cm[r] = ((unsigned)(kc - csq) < 16u) ? 0.f : NEG; }
;     Lay L; lay_init(L, lane);
;     const unsigned kSrc = ((wave & 1) ? L.kOffO : L.kOffE) + 2048u * (unsigned)(wave >> 1), vSrc = L.vOff + 2048u * (unsigned)(wave & 3) + 64u * (unsigned)(wave >> 2);
;     const int kDst = wave * 1024, vDst = 8192 + (wave >> 2) * 4096 + (wave & 3) * 1024;
;     int rdK[4];
;     { const int kq = slab0 + q, kp = (kq & ~9) | ((kq & 1) << 3) | ((kq >> 3) & 1), m = kq & 7;
; #pragma unroll
;       for (int d0 = 0; d0 < 4; ++d0) rdK[d0] = 128 * kp + 16 * ((2 * d0 + hi) ^ m); }
;     const int vrd = 8192 + (slab0 + 4 * hi + ((lane & 15) >> 2)) * 64 + ((lane >> 4) & 1) * 32 + (lane & 3) * 8;
;     LAS char* ring = lds + VST_OFF;
;     const unsigned ringb = (unsigned)(unsigned long long)ring;
;     ...
;     tbl_b(u0, 0, rpb, cshift, lds, tid);
;     UnitB cur, nxt; unit_b(cur, u0, qkv); nxt = cur;
;     if (nu > 1) unit_b(nxt, u0 + 1, qkv);
;     ATT_ROWDMA(cur.Kr, cur.Vr, 0, 0); ATT_ROWDMA(cur.Kr, cur.Vr, 1, 1); ATT_ROWDMA(cur.Kr, cur.Vr, 2, 2);
;     St st;
;     ...
;     ATT_QLOADB(cur);
.LBB0_637:
	s_ashr_i32 s12, s2, 6
	s_and_b32 s14, s12, 3
	s_lshl_b32 s18, s14, 4
	v_and_b32_e32 v10, 15, v190
	v_bfe_u32 v9, v190, 5, 1
	v_or_b32_e32 v11, s18, v10
	v_sub_u32_e64 v2, s18, 8 clamp
	v_min_u32_e32 v12, 32, v2
	v_sub_u32_e64 v2, v11, 8 clamp
	v_lshlrev_b32_e32 v3, 2, v9
	v_min_u32_e32 v2, 48, v2
	v_or_b32_e32 v13, v12, v3
	v_sub_u32_e32 v14, v13, v2
	v_add_u32_e32 v2, 1, v14
	v_mov_b32_e32 v15, 0xf149f2ca
	v_cmp_gt_u32_e32 vcc, 16, v14
	v_add_u32_e32 v4, 2, v14
	s_movk_i32 s15, 0xffef
	v_cndmask_b32_e64 v148, v15, 0, vcc
	v_cmp_gt_u32_e32 vcc, 16, v2
	v_add_u32_e32 v2, 3, v14
	v_lshlrev_b32_e32 v5, 9, v9
	v_cndmask_b32_e64 v149, v15, 0, vcc
	v_cmp_gt_u32_e32 vcc, 16, v2
	v_add_u32_e32 v2, 9, v14
	v_and_b32_e32 v18, 7, v190
	v_cndmask_b32_e64 v151, v15, 0, vcc
	v_cmp_gt_u32_e32 vcc, 16, v4
	v_add_u32_e32 v4, 8, v14
	s_ashr_i32 s19, s2, 8
	v_cndmask_b32_e64 v150, v15, 0, vcc
	v_cmp_gt_u32_e32 vcc, 16, v2
	v_add_u32_e32 v2, 11, v14
	s_bitcmp0_b32 s2, 6
	v_cndmask_b32_e64 v153, v15, 0, vcc
	v_cmp_gt_u32_e32 vcc, 16, v4
	v_add_u32_e32 v4, 10, v14
	v_mov_b32_e32 v161, v147
	v_cndmask_b32_e64 v152, v15, 0, vcc
	v_cmp_gt_u32_e32 vcc, 16, v2
	v_add_u32_e32 v2, 17, v14
	v_mov_b32_e32 v159, v147
	v_cndmask_b32_e64 v155, v15, 0, vcc
	v_cmp_gt_u32_e32 vcc, 16, v4
	v_lshlrev_b32_e32 v4, 7, v190
	v_and_b32_e32 v4, 0x400, v4
	v_cndmask_b32_e64 v154, v15, 0, vcc
	v_cmp_lt_u32_e32 vcc, s15, v14
	s_movk_i32 s15, 0x80
	v_lshrrev_b32_e32 v191, 4, v1
	v_cndmask_b32_e64 v156, v15, 0, vcc
	v_cmp_gt_u32_e32 vcc, 16, v2
	v_bfe_u32 v2, v190, 4, 1
	v_lshlrev_b32_e32 v6, 8, v2
	v_lshlrev_b32_e32 v2, 1, v2
	v_or3_b32 v4, v4, v5, v6
	v_or_b32_e32 v5, v2, v3
	v_bitop3_b32 v2, v2, v18, v3 bitop3:0x36
	v_bitop3_b32 v3, v5, v18, 1 bitop3:0x36
	v_lshlrev_b32_e32 v3, 4, v3
	v_cndmask_b32_e64 v157, v15, 0, vcc
	v_lshlrev_b32_e32 v5, 5, v190
	v_add3_u32 v3, v3, v4, s15
	s_cselect_b64 vcc, -1, 0
	s_lshl_b32 s15, s14, 11
	s_lshl_b32 s22, s19, 6
	v_and_b32_e32 v19, 0x780, v5
	v_lshlrev_b32_e32 v5, 4, v190
	v_lshl_or_b32 v2, v2, 4, v4
	s_lshl_b32 s2, s2, 4
	s_add_i32 s24, s22, s15
	s_lshl_b32 s15, s19, 12
	s_lshl_b32 s14, s14, 10
	v_and_b32_e32 v20, 48, v5
	s_and_b32 s2, s2, 0xfffff800
	v_cndmask_b32_e32 v2, v3, v2, vcc
	s_or_b32 s50, s15, s14
	v_or_b32_e32 v4, v19, v20
	v_add_u32_e32 v160, s2, v2
	s_lshl_b32 s49, s12, 10
	s_addk_i32 s50, 0x2000
	s_add_i32 s2, 0, 0x13900
	v_add_u32_e32 v158, s24, v4
	v_lshl_add_u64 v[2:3], s[26:27], 0, v[160:161]
	s_add_i32 s12, s49, s2
	s_mov_b32 s14, m0
	s_mov_b32 m0, s12
	s_nop 0
	global_load_lds_dwordx4 v[2:3], off
	s_mov_b32 m0, s14
	s_add_i32 s2, s50, s2
	v_lshl_add_u64 v[4:5], s[28:29], 0, v[158:159]
	s_mov_b32 s12, m0
	s_mov_b32 m0, s2
	s_nop 0
	global_load_lds_dwordx4 v[4:5], off
	s_mov_b32 m0, s12
	s_mov_b64 s[14:15], 0x2000
	s_add_i32 s2, 0, 0x17900
	v_lshl_add_u64 v[6:7], v[2:3], 0, s[14:15]
	s_add_i32 s12, s49, s2
	s_mov_b32 s22, m0
	s_mov_b32 m0, s12
	s_nop 0
	global_load_lds_dwordx4 v[6:7], off
	s_mov_b32 m0, s22
	s_add_i32 s2, s50, s2
	s_mov_b64 s[22:23], 0x4000
	v_lshl_add_u64 v[6:7], v[4:5], 0, s[14:15]
	s_mov_b32 s12, m0
	s_mov_b32 m0, s2
	s_nop 0
	global_load_lds_dwordx4 v[6:7], off
	s_mov_b32 m0, s12
	v_lshl_add_u64 v[2:3], v[2:3], 0, s[22:23]
	s_add_i32 s2, 0, 0x1b900
	s_lshl_b32 s51, s19, 1
	s_add_i32 s12, s49, s2
	s_mov_b32 s25, m0
	s_mov_b32 m0, s12
	s_nop 0
	global_load_lds_dwordx4 v[2:3], off
	s_mov_b32 m0, s25
	v_lshl_add_u64 v[2:3], v[4:5], 0, s[22:23]
	v_or_b32_e32 v192, s51, v191
	s_add_i32 s2, s50, s2
	s_mov_b32 s12, m0
	s_mov_b32 m0, s2
	s_nop 0
	global_load_lds_dwordx4 v[2:3], off
	s_mov_b32 m0, s12
	v_lshlrev_b32_e32 v2, 6, v192
	s_mov_b32 s13, 0
	s_lshl_b32 s12, s59, 9
	v_ashrrev_i32_e32 v163, 31, v2
	v_or_b32_e32 v162, v2, v11
	v_lshl_add_u64 v[2:3], v[162:163], 0, s[12:13]
	v_lshlrev_b64 v[2:3], 7, v[2:3]
	v_lshl_add_u64 v[2:3], s[16:17], 0, v[2:3]
	v_lshlrev_b32_e32 v146, 4, v9
	v_lshl_add_u64 v[2:3], v[2:3], 0, v[146:147]
	s_mov_b32 s2, 0x8000
	s_mov_b64 s[16:17], 0x8000
	v_add_co_u32_e32 v6, vcc, s2, v2
	v_lshl_add_u64 v[4:5], v[2:3], 0, s[16:17]
	s_nop 0
	v_addc_co_u32_e32 v7, vcc, 0, v3, vcc
	global_load_dwordx4 v[80:83], v[2:3], off
	global_load_dwordx4 v[84:87], v[2:3], off offset:32
	global_load_dwordx4 v[88:91], v[4:5], off offset:32
	global_load_dwordx4 v[92:95], v[4:5], off offset:64
	global_load_dwordx4 v[96:99], v[2:3], off offset:64
	global_load_dwordx4 v[100:103], v[2:3], off offset:96
	global_load_dwordx4 v[104:107], v[6:7], off
	global_load_dwordx4 v[108:111], v[4:5], off offset:96
	v_add_u32_e32 v16, 19, v14
	v_add_u32_e32 v17, 18, v14
	v_cmp_gt_u32_e32 vcc, 16, v16
	v_add_u32_e32 v2, 25, v14
	v_add_u32_e32 v3, 24, v14
	v_cndmask_b32_e64 v165, v15, 0, vcc
	v_cmp_gt_u32_e32 vcc, 16, v17
	v_lshrrev_b32_e32 v5, 5, v162
	v_bitop3_b32 v5, v5, v162, 15 bitop3:0x6c
	v_cndmask_b32_e64 v164, v15, 0, vcc
	v_cmp_gt_u32_e32 vcc, 16, v2
	v_add_u32_e32 v2, 27, v14
	s_movk_i32 s52, 0x88
	v_cndmask_b32_e64 v167, v15, 0, vcc
	v_cmp_gt_u32_e32 vcc, 16, v3
	v_add_u32_e32 v3, 26, v14
	s_waitcnt lgkmcnt(0)
	s_barrier
; #define LAS __attribute__((address_space(3)))
; __device__ __forceinline__ void attn_b_phase(Frame& F, const float cshift, const bf16* qkv, const bf16* gate, bf16* y, const float* rpb, const float* qg, const float* kg) {
;     ...
;     float cm[16];
; #pragma unroll
;     for (int r = 0; r < 16; ++r) { const int kc = slab0 + (r & 3) + 8 * (r >> 2) + 4 * hi; cm[r] = ((unsigned)(kc - csq) < 16u) ? 0.f : NEG; }
;     Lay L; lay_init(L, lane);
;     const unsigned kSrc = ((wave & 1) ? L.kOffO : L.kOffE) + 2048u * (unsigned)(wave >> 1), vSrc = L.vOff + 2048u * (unsigned)(wave & 3) + 64u * (unsigned)(wave >> 2);
;     const int kDst = wave * 1024, vDst = 8192 + (wave >> 2) * 4096 + (wave & 3) * 1024;
;     int rdK[4];
;     { const int kq = slab0 + q, kp = (kq & ~9) | ((kq & 1) << 3) | ((kq >> 3) & 1), m = kq & 7;
; #pragma unroll
;       for (int d0 = 0; d0 < 4; ++d0) rdK[d0] = 128 * kp + 16 * ((2 * d0 + hi) ^ m); }
;     const int vrd = 8192 + (slab0 + 4 * hi + ((lane & 15) >> 2)) * 64 + ((lane >> 4) & 1) * 32 + (lane & 3) * 8;
;     LAS char* ring = lds + VST_OFF;
	v_cndmask_b32_e64 v166, v15, 0, vcc
	v_cmp_gt_u32_e32 vcc, 16, v2
	v_add_u32_e32 v2, v12, v1
	v_lshlrev_b32_e32 v4, 3, v2
	v_cndmask_b32_e64 v169, v15, 0, vcc
	v_cmp_gt_u32_e32 vcc, 16, v3
	v_and_b32_e32 v3, 0x76, v2
	v_and_b32_e32 v4, 8, v4
	v_bfe_u32 v2, v2, 3, 1
	v_or3_b32 v2, v4, v3, v2
	v_lshlrev_b32_e32 v193, 7, v2
	v_bitop3_b32 v2, v9, v190, 7 bitop3:0x78
	v_lshlrev_b32_e32 v194, 4, v2
	v_bitop3_b32 v2, v9, v18, 2 bitop3:0x36
	v_lshlrev_b32_e32 v195, 4, v2
	v_bitop3_b32 v2, v9, v18, 4 bitop3:0x36
	v_cndmask_b32_e64 v168, v15, 0, vcc
	v_lshlrev_b32_e32 v196, 4, v2
	v_bitop3_b32 v2, v9, v18, 6 bitop3:0x36
	v_lshrrev_b32_e32 v3, 2, v190
	v_add_u32_e32 v4, 0x100, v162
	v_cmp_eq_u32_e32 vcc, 15, v1
	v_sub_u32_e32 v1, v13, v10
	v_lshlrev_b32_e32 v197, 4, v2
	v_and_or_b32 v2, v3, 3, v13
	v_lshrrev_b32_e32 v6, 5, v4
	v_subrev_u32_e32 v1, s18, v1
	v_lshlrev_b32_e32 v198, 6, v2
	v_lshlrev_b32_e32 v2, 1, v190
	v_bitop3_b32 v6, v6, v4, 15 bitop3:0x6c
	v_lshl_add_u32 v1, v1, 2, 0
	v_and_b32_e32 v199, 32, v2
	v_lshlrev_b32_e32 v2, 3, v190
	v_mul_lo_u32 v5, v5, s52
	v_mul_lo_u32 v6, v6, s52
	v_add_u32_e32 v203, 0x119fc, v1
	v_add_u32_e32 v1, s24, v19
	v_readlane_b32 s72, v253, 6
	v_and_b32_e32 v8, 63, v190
	v_and_b32_e32 v200, 24, v2
	v_lshlrev_b32_e32 v2, 3, v9
	v_add_u32_e32 v5, 0, v5
	v_and_b32_e32 v3, 8, v3
	v_add_u32_e32 v6, 0, v6
	v_or_b32_e32 v146, v1, v20
	s_mov_b64 s[18:19], 0x6000
	v_readlane_b32 s78, v253, 12
	v_readlane_b32 s79, v253, 13
	v_cmp_gt_u32_e64 s[36:37], 32, v8
	v_lshl_add_u32 v201, v162, 2, s90
	v_lshl_add_u32 v202, v4, 2, s90
	v_lshl_add_u64 v[170:171], v[146:147], 0, s[18:19]
	v_lshl_add_u64 v[172:173], v[160:161], 0, s[18:19]
	v_add_u32_e32 v204, 0xfffffe00, v190
	v_add_u32_e32 v205, 0x11800, v0
	s_movk_i32 s53, 0x1000
	v_lshlrev_b32_e32 v174, 1, v2
	v_add_u32_e32 v206, v5, v3
	v_add_u32_e32 v207, v6, v3
	s_xor_b64 s[18:19], vcc, -1
	s_mov_b32 s54, 0
	s_mov_b32 s55, 0
	s_mov_b32 s57, 0
	s_mov_b64 s[70:71], s[78:79]
	v_readlane_b32 s73, v253, 7
	v_readlane_b32 s74, v253, 8
	v_readlane_b32 s75, v253, 9
	v_readlane_b32 s76, v253, 10
	v_readlane_b32 s77, v253, 11
	s_waitcnt vmcnt(0)
	s_branch .LBB0_639

; __device__ __forceinline__ void attn_b_phase(Frame& F, const float cshift, const bf16* qkv, const bf16* gate, bf16* y, const float* rpb, const float* qg, const float* kg) {
;     ...
;     for (int ui = 0; ui < nu; ++ui) {
;         const int u = u0 + ui;
;         const bool more = (ui + 1 < nu);
;         const int R = cur.R, gr0 = 8 * R + 2 * wq, kr0 = min(max(8 * R - 4, 0), 56), nrows = cur.nrows;
;         const int grA = gr0 + (q >> 4), grB = grA + 4;
;         const int tlocA = (2 * wq + (q >> 4)) * 64 + gcq, tlocB = tlocA + 256;
;         Seg sg;
;         sg.raLo = min(max(grA - 4, 0), 56) - kr0; sg.rbLo = min(max(grB - 4, 0), 56) - kr0;
;         sg.tbA = lds + TBL_OFF + (ui & 1) * TBL_BYTES + 4 * (16 + (kr0 - grA + 7) * 32 + (slab0 + 4 * hi - gcq + 15)); sg.tbB = sg.tbA - 4 * 128;
;         sg.tneg = lds + TBL_OFF + (ui & 1) * TBL_BYTES + 4 * 576;
;         const int aLo = min(max(gr0 - 4, 0), 56) - kr0, aHi = min(max(gr0 + 1 - 4, 0), 56) + 7 - kr0, bLo = min(max(gr0 + 4 - 4, 0), 56) - kr0, bHi = min(max(gr0 + 5 - 4, 0), 56) + 7 - kr0;
; #pragma unroll
;         for (int d0 = 0; d0 < 4; ++d0) asm volatile("" : "+v"(st.qA[d0]), "+v"(st.qB[d0]));
;         f32x16 oA0 = f32x16{}, oA1 = f32x16{}, oB0 = f32x16{}, oB1 = f32x16{}; float lA = 0.f, lB = 0.f;
.LBB0_639:
	s_add_i32 s56, s57, 1
	s_cmp_ge_i32 s56, s42
	s_cselect_b64 s[22:23], -1, 0
	s_cmp_lt_i32 s56, s42
	s_cselect_b64 s[24:25], -1, 0
	s_cmp_lt_i32 s21, 1
	s_waitcnt vmcnt(8)
	s_waitcnt vmcnt(8)
	s_cbranch_scc1 .LBB0_668
	s_lshl_b32 s63, s59, 3
	s_max_i32 s12, s63, 4
	s_add_i32 s12, s12, -4
	s_add_i32 s2, s63, s51
	s_min_u32 s64, s12, 56
	s_lshl_b32 s12, s57, 12
	v_or_b32_e32 v0, s2, v191
	s_and_b32 s12, s12, 0x1000
	s_max_i32 s38, s2, 4
	s_max_i32 s39, s2, 3
	v_med3_i32 v1, s2, 0, 56
	s_or_b32 s2, s2, 1
	v_med3_i32 v0, v0, 0, 56
	s_add_i32 s12, s12, 0
	s_add_i32 s38, s38, -4
	s_add_i32 s39, s39, -3
	v_med3_i32 v2, s2, 0, 56
	s_min_u32 s38, s38, 56
	s_min_u32 s39, s39, 56
	v_sub_u32_e32 v175, s64, v0
	s_add_i32 s2, s12, 0x12100
	v_subrev_u32_e32 v0, s64, v2
	s_add_i32 s12, s21, -1
	s_sub_i32 s60, s38, s64
	s_sub_i32 s61, s39, s64
	v_subrev_u32_e32 v208, s64, v1
	v_add_u32_e32 v209, 7, v0
	v_lshl_add_u64 v[0:1], s[26:27], 0, v[160:161]
	s_lshl_b64 s[38:39], s[12:13], 13
	v_lshl_add_u64 v[182:183], v[0:1], 0, s[38:39]
	v_add_u32_e32 v0, s63, v192
	v_lshl_add_u64 v[2:3], s[28:29], 0, v[158:159]
	v_lshlrev_b32_e32 v1, 7, v0
	v_max_i32_e32 v0, 4, v0
	s_and_b32 s62, s54, 0x1000
	v_lshl_add_u64 v[184:185], v[2:3], 0, s[38:39]
	s_lshl_b32 s38, s64, 7
	v_add_u32_e32 v0, -4, v0
	s_add_i32 s62, s62, s38
	v_min_u32_e32 v0, 56, v0
	v_mov_b32_e32 v46, v147
	v_mov_b32_e32 v47, v147
	v_sub_u32_e32 v1, s62, v1
	v_sub_u32_e32 v211, s64, v0
	v_mov_b32_e32 v146, v147
	v_mov_b32_e32 v32, v147
	v_mov_b32_e32 v33, v147
	v_mov_b32_e32 v34, v147
	v_mov_b32_e32 v35, v147
	v_mov_b32_e32 v36, v147
	v_mov_b32_e32 v37, v147
	v_mov_b32_e32 v38, v147
	v_mov_b32_e32 v39, v147
	v_mov_b32_e32 v40, v147
	v_mov_b32_e32 v41, v147
	v_mov_b32_e32 v42, v147
	v_mov_b32_e32 v43, v147
	v_mov_b32_e32 v44, v147
	v_mov_b32_e32 v45, v147
	v_mov_b32_e32 v0, 0
	v_mov_b64_e32 v[62:63], v[46:47]
	s_add_i32 s61, s61, 7
	v_lshl_add_u64 v[178:179], s[8:9], 0, v[160:161]
	v_lshl_add_u64 v[180:181], s[10:11], 0, v[158:159]
	s_lshl_b32 s12, s55, 14
	v_add_u32_e32 v210, v203, v1
	v_readlane_b32 s64, v252, 40
	s_sub_i32 s62, 0, s21
	v_lshl_add_u64 v[186:187], s[28:29], 0, v[170:171]
	v_lshl_add_u64 v[188:189], s[26:27], 0, v[172:173]
	s_mov_b32 s63, 0
	v_mov_b64_e32 v[60:61], v[44:45]
	v_mov_b64_e32 v[58:59], v[42:43]
	v_mov_b64_e32 v[56:57], v[40:41]
	v_mov_b64_e32 v[54:55], v[38:39]
	v_mov_b64_e32 v[52:53], v[36:37]
	v_mov_b64_e32 v[50:51], v[34:35]
	v_mov_b64_e32 v[48:49], v[32:33]
	v_mov_b64_e32 v[176:177], v[146:147]
	v_mov_b32_e32 v1, v0
	v_mov_b32_e32 v2, v0
	v_mov_b32_e32 v3, v0
	v_mov_b32_e32 v4, v0
	v_mov_b32_e32 v5, v0
	v_mov_b32_e32 v6, v0
	v_mov_b32_e32 v7, v0
	v_mov_b32_e32 v8, v0
	v_mov_b32_e32 v9, v0
	v_mov_b32_e32 v10, v0
	v_mov_b32_e32 v11, v0
	v_mov_b32_e32 v12, v0
	v_mov_b32_e32 v13, v0
	v_mov_b32_e32 v14, v0
	v_mov_b32_e32 v15, v0
	v_mov_b32_e32 v16, v0
	v_mov_b32_e32 v17, v0
	v_mov_b32_e32 v18, v0
	v_mov_b32_e32 v19, v0
	v_mov_b32_e32 v20, v0
	v_mov_b32_e32 v21, v0
	v_mov_b32_e32 v22, v0
	v_mov_b32_e32 v23, v0
	v_mov_b32_e32 v24, v0
	v_mov_b32_e32 v25, v0
	v_mov_b32_e32 v26, v0
	v_mov_b32_e32 v27, v0
	v_mov_b32_e32 v28, v0
	v_mov_b32_e32 v29, v0
	v_mov_b32_e32 v30, v0
	v_mov_b32_e32 v31, v0
	s_branch .LBB0_642
